# gate-tile stores sc0; + no entry grid.sync
# baseline (speedup 1.0000x reference)
; __device__ __forceinline__ float sigm(float v) { return __builtin_amdgcn_rcpf(1.0f + __builtin_amdgcn_exp2f(-LOG2E * v)); }
; __device__ __forceinline__ unsigned cvt_pk_bf16(float lo, float hi) { f32x2_t v = {lo, hi}; bf16x2_t b = __builtin_convertvector(v, bf16x2_t); return __builtin_bit_cast(unsigned, b); }
; template <int MODE> __device__ __forceinline__ float actf(float v) {
;     if (MODE == 1) return v * sigm(v);
;     if (MODE == 2) return fminf(1.0f + __builtin_amdgcn_exp2f(-LOG2E * v), 1e30f);
;     template <int MODE> __device__ __forceinline__ void run(const f32x4 (&acc)[2][2][4][2], const Unit& u, int wr, int wc, int fr, int fq) const {
;     ...
;         char* base = (MODE == 2) ? (char*)(O + (size_t)6 * ((size_t)MTOK * 512)) + ((size_t)(((pn - 12) * 128 + u.pm) * 8 + wid__)) * 16384
;                                  : (char*)(O + (size_t)t * ((size_t)MTOK * 512) + (size_t)u.pm * BM * 512 + (colt & 511));
;         unsigned off0 = (MODE == 2) ? (unsigned)((t__ & 63) * 16) : (unsigned)((wr * 64 + fr) * 512 + wc * 32 + 8 * fq) * 2u; asm volatile("" : "+v"(off0));
; #pragma unroll
;         for (int bj = 0; bj < 2; ++bj) {
; #pragma unroll
;             for (int ai = 0; ai < 2; ++ai)
; #pragma unroll
;                 for (int m = 0; m < 4; ++m) { const unsigned off = off0 + ((MODE == 2) ? (unsigned)(((ai * 4 + m) * 2 + bj) * 1024) : (unsigned)((ai * HALF + m * 16) * 512 + bj * HALF) * 2u);
;                     const f32x4 v0 = acc[ai][bj][m][0], v1 = acc[ai][bj][m][1];
;                     u32x4 w; w.x = cvt_pk_bf16(actf<MODE>(v0[0]), actf<MODE>(v0[1])); w.y = cvt_pk_bf16(actf<MODE>(v0[2]), actf<MODE>(v0[3]));
;                     w.z = cvt_pk_bf16(actf<MODE>(v1[0]), actf<MODE>(v1[1])); w.w = cvt_pk_bf16(actf<MODE>(v1[2]), actf<MODE>(v1[3]));
;                     *(u32x4*)(base + off) = w; }
.LBB0_403:
	v_mul_f32_e32 v12, 0xbfb8aa3b, v12
	v_mul_f32_e32 v13, 0xbfb8aa3b, v13
	v_exp_f32_e32 v12, v12
	v_exp_f32_e32 v13, v13
	v_mul_f32_e32 v14, 0xbfb8aa3b, v14
	v_mul_f32_e32 v15, 0xbfb8aa3b, v15
	v_mul_f32_e32 v8, 0xbfb8aa3b, v8
	v_mul_f32_e32 v9, 0xbfb8aa3b, v9
	v_exp_f32_e32 v14, v14
	v_exp_f32_e32 v15, v15
	v_exp_f32_e32 v8, v8
	v_exp_f32_e32 v9, v9
	v_mul_f32_e32 v10, 0xbfb8aa3b, v10
	v_mul_f32_e32 v11, 0xbfb8aa3b, v11
	v_add_f32_e32 v12, 1.0, v12
	v_add_f32_e32 v13, 1.0, v13
	v_exp_f32_e32 v10, v10
	v_exp_f32_e32 v11, v11
	v_mul_f32_e32 v76, 0xbfb8aa3b, v76
	v_mul_f32_e32 v77, 0xbfb8aa3b, v77
	v_min_f32_e32 v12, 0x7149f2ca, v12
	v_min_f32_e32 v13, 0x7149f2ca, v13
	v_exp_f32_e32 v76, v76
	v_exp_f32_e32 v77, v77
	v_cvt_pk_bf16_f32 v12, v12, v13
	v_add_f32_e32 v13, 1.0, v14
	v_add_f32_e32 v14, 1.0, v15
	v_add_f32_e32 v8, 1.0, v8
	v_add_f32_e32 v9, 1.0, v9
	v_mul_f32_e32 v78, 0xbfb8aa3b, v78
	v_mul_f32_e32 v79, 0xbfb8aa3b, v79
	v_mul_f32_e32 v72, 0xbfb8aa3b, v72
	v_mul_f32_e32 v73, 0xbfb8aa3b, v73
	v_min_f32_e32 v13, 0x7149f2ca, v13
	v_min_f32_e32 v14, 0x7149f2ca, v14
	v_min_f32_e32 v8, 0x7149f2ca, v8
	v_min_f32_e32 v9, 0x7149f2ca, v9
	v_mov_b32_e32 v142, v212
	s_lshl_b32 s60, s72, 7
	v_exp_f32_e32 v78, v78
	v_exp_f32_e32 v79, v79
	v_exp_f32_e32 v72, v72
	v_exp_f32_e32 v73, v73
	v_cvt_pk_bf16_f32 v13, v13, v14
	v_cvt_pk_bf16_f32 v14, v8, v9
	v_add_f32_e32 v8, 1.0, v10
	v_add_f32_e32 v9, 1.0, v11
	s_add_i32 s60, s60, s54
	v_readfirstlane_b32 s55, v142
	v_mul_f32_e32 v74, 0xbfb8aa3b, v74
	v_mul_f32_e32 v75, 0xbfb8aa3b, v75
	v_min_f32_e32 v8, 0x7149f2ca, v8
	v_min_f32_e32 v9, 0x7149f2ca, v9
	s_ashr_i32 s55, s55, 6
	s_lshl_b32 s54, s60, 3
	v_add_f32_e32 v76, 1.0, v76
	v_add_f32_e32 v77, 1.0, v77
	v_exp_f32_e32 v74, v74
	v_exp_f32_e32 v75, v75
	v_cvt_pk_bf16_f32 v15, v8, v9
	v_mul_f32_e32 v8, 0xbfb8aa3b, v68
	v_mul_f32_e32 v9, 0xbfb8aa3b, v69
	s_add_i32 s54, s54, s55
	v_min_f32_e32 v76, 0x7149f2ca, v76
	v_min_f32_e32 v77, 0x7149f2ca, v77
	v_exp_f32_e32 v8, v8
	v_exp_f32_e32 v9, v9
	s_addk_i32 s54, 0xd000
	v_cvt_pk_bf16_f32 v76, v76, v77
	v_add_f32_e32 v77, 1.0, v78
	v_add_f32_e32 v78, 1.0, v79
	v_add_f32_e32 v72, 1.0, v72
	v_add_f32_e32 v73, 1.0, v73
	v_mul_f32_e32 v10, 0xbfb8aa3b, v70
	v_mul_f32_e32 v11, 0xbfb8aa3b, v71
	s_ashr_i32 s55, s54, 31
	v_min_f32_e32 v77, 0x7149f2ca, v77
	v_min_f32_e32 v78, 0x7149f2ca, v78
	v_min_f32_e32 v72, 0x7149f2ca, v72
	v_min_f32_e32 v73, 0x7149f2ca, v73
	v_exp_f32_e32 v10, v10
	v_exp_f32_e32 v11, v11
	s_lshl_b64 s[54:55], s[54:55], 14
	v_lshlrev_b32_e32 v142, 4, v142
	v_cvt_pk_bf16_f32 v77, v77, v78
	v_cvt_pk_bf16_f32 v78, v72, v73
	v_add_f32_e32 v72, 1.0, v74
	v_add_f32_e32 v73, 1.0, v75
	s_add_u32 s54, s33, s54
	v_and_b32_e32 v142, 0x3f0, v142
	v_min_f32_e32 v72, 0x7149f2ca, v72
	v_min_f32_e32 v73, 0x7149f2ca, v73
	v_add_f32_e32 v8, 1.0, v8
	v_add_f32_e32 v9, 1.0, v9
	s_addc_u32 s55, s37, s55
	v_cvt_pk_bf16_f32 v79, v72, v73
	v_add_u32_e32 v72, 0x3800, v142
	v_min_f32_e32 v8, 0x7149f2ca, v8
	v_min_f32_e32 v9, 0x7149f2ca, v9
	v_mul_f32_e32 v126, 0xbfb8aa3b, v126
	v_mul_f32_e32 v127, 0xbfb8aa3b, v127
	v_mul_f32_e32 v118, 0xbfb8aa3b, v118
	v_mul_f32_e32 v119, 0xbfb8aa3b, v119
	v_mul_f32_e32 v110, 0xbfb8aa3b, v110
	v_mul_f32_e32 v111, 0xbfb8aa3b, v111
	v_mul_f32_e32 v102, 0xbfb8aa3b, v102
	v_mul_f32_e32 v103, 0xbfb8aa3b, v103
	v_mul_f32_e32 v92, 0xbfb8aa3b, v92
	v_mul_f32_e32 v93, 0xbfb8aa3b, v93
	v_mul_f32_e32 v84, 0xbfb8aa3b, v84
	v_mul_f32_e32 v85, 0xbfb8aa3b, v85
	global_store_dwordx4 v72, v[12:15], s[54:55] sc0
	v_cvt_pk_bf16_f32 v8, v8, v9
	v_add_f32_e32 v9, 1.0, v10
	v_add_f32_e32 v10, 1.0, v11
	v_mul_f32_e32 v11, 0xbfb8aa3b, v64
	v_mul_f32_e32 v13, 0xbfb8aa3b, v65
	v_exp_f32_e32 v126, v126
	v_exp_f32_e32 v127, v127
	v_exp_f32_e32 v118, v118
	v_exp_f32_e32 v119, v119
	v_exp_f32_e32 v110, v110
	v_exp_f32_e32 v111, v111
	v_exp_f32_e32 v102, v102
	v_exp_f32_e32 v103, v103
	v_exp_f32_e32 v92, v92
	v_exp_f32_e32 v93, v93
	v_exp_f32_e32 v84, v84
	v_exp_f32_e32 v85, v85
	v_exp_f32_e32 v11, v11
	v_exp_f32_e32 v13, v13
	v_mul_f32_e32 v128, 0xbfb8aa3b, v128
	v_mul_f32_e32 v129, 0xbfb8aa3b, v129
	v_mul_f32_e32 v122, 0xbfb8aa3b, v122
	v_mul_f32_e32 v123, 0xbfb8aa3b, v123
	v_mul_f32_e32 v120, 0xbfb8aa3b, v120
	v_mul_f32_e32 v121, 0xbfb8aa3b, v121
	v_mul_f32_e32 v114, 0xbfb8aa3b, v114
	v_mul_f32_e32 v115, 0xbfb8aa3b, v115
	v_mul_f32_e32 v112, 0xbfb8aa3b, v112
	v_mul_f32_e32 v113, 0xbfb8aa3b, v113
	v_mul_f32_e32 v106, 0xbfb8aa3b, v106
	v_mul_f32_e32 v107, 0xbfb8aa3b, v107
	v_mul_f32_e32 v104, 0xbfb8aa3b, v104
	v_mul_f32_e32 v105, 0xbfb8aa3b, v105
	v_mul_f32_e32 v98, 0xbfb8aa3b, v98
	v_mul_f32_e32 v99, 0xbfb8aa3b, v99
	v_mul_f32_e32 v94, 0xbfb8aa3b, v94
	v_mul_f32_e32 v95, 0xbfb8aa3b, v95
	v_mul_f32_e32 v88, 0xbfb8aa3b, v88
	v_mul_f32_e32 v89, 0xbfb8aa3b, v89
	v_mul_f32_e32 v86, 0xbfb8aa3b, v86
	v_mul_f32_e32 v87, 0xbfb8aa3b, v87
	v_mul_f32_e32 v80, 0xbfb8aa3b, v80
	v_mul_f32_e32 v81, 0xbfb8aa3b, v81
	v_exp_f32_e32 v128, v128
	v_exp_f32_e32 v129, v129
	v_exp_f32_e32 v122, v122
	v_exp_f32_e32 v123, v123
	v_exp_f32_e32 v120, v120
	v_exp_f32_e32 v121, v121
	v_exp_f32_e32 v114, v114
	v_exp_f32_e32 v115, v115
	v_exp_f32_e32 v112, v112
	v_exp_f32_e32 v113, v113
	v_exp_f32_e32 v106, v106
	v_exp_f32_e32 v107, v107
	v_exp_f32_e32 v104, v104
	v_exp_f32_e32 v105, v105
	v_exp_f32_e32 v98, v98
	v_exp_f32_e32 v99, v99
	v_exp_f32_e32 v94, v94
	v_exp_f32_e32 v95, v95
	v_exp_f32_e32 v88, v88
	v_exp_f32_e32 v89, v89
	v_exp_f32_e32 v86, v86
	v_exp_f32_e32 v87, v87
	v_exp_f32_e32 v80, v80
	v_exp_f32_e32 v81, v81
	v_mul_f32_e32 v124, 0xbfb8aa3b, v124
	v_mul_f32_e32 v125, 0xbfb8aa3b, v125
	v_mul_f32_e32 v116, 0xbfb8aa3b, v116
; __device__ __forceinline__ unsigned cvt_pk_bf16(float lo, float hi) { f32x2_t v = {lo, hi}; bf16x2_t b = __builtin_convertvector(v, bf16x2_t); return __builtin_bit_cast(unsigned, b); }
;     template <int MODE> __device__ __forceinline__ void run(const f32x4 (&acc)[2][2][4][2], const Unit& u, int wr, int wc, int fr, int fq) const {
;     ...
;                 for (int m = 0; m < 4; ++m) { const unsigned off = off0 + ((MODE == 2) ? (unsigned)(((ai * 4 + m) * 2 + bj) * 1024) : (unsigned)((ai * HALF + m * 16) * 512 + bj * HALF) * 2u);
;                     const f32x4 v0 = acc[ai][bj][m][0], v1 = acc[ai][bj][m][1];
;                     u32x4 w; w.x = cvt_pk_bf16(actf<MODE>(v0[0]), actf<MODE>(v0[1])); w.y = cvt_pk_bf16(actf<MODE>(v0[2]), actf<MODE>(v0[3]));
;                     w.z = cvt_pk_bf16(actf<MODE>(v1[0]), actf<MODE>(v1[1])); w.w = cvt_pk_bf16(actf<MODE>(v1[2]), actf<MODE>(v1[3]));
;                     *(u32x4*)(base + off) = w; }
	v_mul_f32_e32 v117, 0xbfb8aa3b, v117
	v_mul_f32_e32 v108, 0xbfb8aa3b, v108
	v_mul_f32_e32 v109, 0xbfb8aa3b, v109
	v_mul_f32_e32 v100, 0xbfb8aa3b, v100
	v_mul_f32_e32 v101, 0xbfb8aa3b, v101
	v_mul_f32_e32 v90, 0xbfb8aa3b, v90
	v_mul_f32_e32 v91, 0xbfb8aa3b, v91
	v_mul_f32_e32 v82, 0xbfb8aa3b, v82
	v_mul_f32_e32 v83, 0xbfb8aa3b, v83
	v_min_f32_e32 v9, 0x7149f2ca, v9
	v_min_f32_e32 v10, 0x7149f2ca, v10
	v_add_f32_e32 v126, 1.0, v126
	v_add_f32_e32 v127, 1.0, v127
	v_exp_f32_e32 v124, v124
	v_exp_f32_e32 v125, v125
	v_add_f32_e32 v118, 1.0, v118
	v_add_f32_e32 v119, 1.0, v119
	v_exp_f32_e32 v116, v116
	v_exp_f32_e32 v117, v117
	v_add_f32_e32 v110, 1.0, v110
	v_add_f32_e32 v111, 1.0, v111
	v_exp_f32_e32 v108, v108
	v_exp_f32_e32 v109, v109
	v_add_f32_e32 v102, 1.0, v102
	v_add_f32_e32 v103, 1.0, v103
	v_exp_f32_e32 v100, v100
	v_exp_f32_e32 v101, v101
	v_add_f32_e32 v92, 1.0, v92
	v_add_f32_e32 v93, 1.0, v93
	v_exp_f32_e32 v90, v90
	v_exp_f32_e32 v91, v91
	v_add_f32_e32 v84, 1.0, v84
	v_add_f32_e32 v85, 1.0, v85
	v_exp_f32_e32 v82, v82
	v_exp_f32_e32 v83, v83
	v_cvt_pk_bf16_f32 v9, v9, v10
	v_add_f32_e32 v10, 1.0, v11
	v_add_f32_e32 v11, 1.0, v13
	v_mul_f32_e32 v13, 0xbfb8aa3b, v66
	v_mul_f32_e32 v14, 0xbfb8aa3b, v67
	v_min_f32_e32 v126, 0x7149f2ca, v126
	v_min_f32_e32 v127, 0x7149f2ca, v127
	v_min_f32_e32 v118, 0x7149f2ca, v118
	v_min_f32_e32 v119, 0x7149f2ca, v119
	v_min_f32_e32 v110, 0x7149f2ca, v110
	v_min_f32_e32 v111, 0x7149f2ca, v111
	v_min_f32_e32 v102, 0x7149f2ca, v102
	v_min_f32_e32 v103, 0x7149f2ca, v103
	v_min_f32_e32 v92, 0x7149f2ca, v92
	v_min_f32_e32 v93, 0x7149f2ca, v93
	v_min_f32_e32 v84, 0x7149f2ca, v84
	v_min_f32_e32 v85, 0x7149f2ca, v85
	v_exp_f32_e32 v13, v13
	v_exp_f32_e32 v14, v14
	v_cvt_pk_bf16_f32 v126, v126, v127
	v_add_f32_e32 v127, 1.0, v128
	v_add_f32_e32 v128, 1.0, v129
	v_add_f32_e32 v122, 1.0, v122
	v_add_f32_e32 v123, 1.0, v123
	v_cvt_pk_bf16_f32 v118, v118, v119
	v_add_f32_e32 v119, 1.0, v120
	v_add_f32_e32 v120, 1.0, v121
	v_add_f32_e32 v114, 1.0, v114
	v_add_f32_e32 v115, 1.0, v115
	v_cvt_pk_bf16_f32 v110, v110, v111
	v_add_f32_e32 v111, 1.0, v112
	v_add_f32_e32 v112, 1.0, v113
	v_add_f32_e32 v106, 1.0, v106
	v_add_f32_e32 v107, 1.0, v107
	v_cvt_pk_bf16_f32 v102, v102, v103
	v_add_f32_e32 v103, 1.0, v104
	v_add_f32_e32 v104, 1.0, v105
	v_add_f32_e32 v98, 1.0, v98
	v_add_f32_e32 v99, 1.0, v99
	v_cvt_pk_bf16_f32 v92, v92, v93
	v_add_f32_e32 v93, 1.0, v94
	v_add_f32_e32 v94, 1.0, v95
	v_add_f32_e32 v88, 1.0, v88
	v_add_f32_e32 v89, 1.0, v89
	v_cvt_pk_bf16_f32 v84, v84, v85
	v_add_f32_e32 v85, 1.0, v86
	v_add_f32_e32 v86, 1.0, v87
	v_add_f32_e32 v80, 1.0, v80
	v_add_f32_e32 v81, 1.0, v81
	v_min_f32_e32 v127, 0x7149f2ca, v127
	v_min_f32_e32 v128, 0x7149f2ca, v128
	v_min_f32_e32 v122, 0x7149f2ca, v122
	v_min_f32_e32 v123, 0x7149f2ca, v123
	v_min_f32_e32 v119, 0x7149f2ca, v119
	v_min_f32_e32 v120, 0x7149f2ca, v120
	v_min_f32_e32 v114, 0x7149f2ca, v114
	v_min_f32_e32 v115, 0x7149f2ca, v115
	v_min_f32_e32 v111, 0x7149f2ca, v111
	v_min_f32_e32 v112, 0x7149f2ca, v112
	v_min_f32_e32 v106, 0x7149f2ca, v106
	v_min_f32_e32 v107, 0x7149f2ca, v107
	v_min_f32_e32 v103, 0x7149f2ca, v103
	v_min_f32_e32 v104, 0x7149f2ca, v104
	v_min_f32_e32 v98, 0x7149f2ca, v98
	v_min_f32_e32 v99, 0x7149f2ca, v99
	v_min_f32_e32 v93, 0x7149f2ca, v93
	v_min_f32_e32 v94, 0x7149f2ca, v94
	v_min_f32_e32 v88, 0x7149f2ca, v88
	v_min_f32_e32 v89, 0x7149f2ca, v89
	v_min_f32_e32 v85, 0x7149f2ca, v85
	v_min_f32_e32 v86, 0x7149f2ca, v86
	v_min_f32_e32 v80, 0x7149f2ca, v80
	v_min_f32_e32 v81, 0x7149f2ca, v81
	v_cvt_pk_bf16_f32 v127, v127, v128
	v_cvt_pk_bf16_f32 v128, v122, v123
	v_add_f32_e32 v122, 1.0, v124
	v_add_f32_e32 v123, 1.0, v125
	v_cvt_pk_bf16_f32 v119, v119, v120
	v_cvt_pk_bf16_f32 v120, v114, v115
	v_add_f32_e32 v114, 1.0, v116
	v_add_f32_e32 v115, 1.0, v117
	v_cvt_pk_bf16_f32 v111, v111, v112
	v_cvt_pk_bf16_f32 v112, v106, v107
	v_add_f32_e32 v106, 1.0, v108
	v_add_f32_e32 v107, 1.0, v109
	v_cvt_pk_bf16_f32 v103, v103, v104
	v_cvt_pk_bf16_f32 v104, v98, v99
	v_add_f32_e32 v98, 1.0, v100
	v_add_f32_e32 v99, 1.0, v101
	v_cvt_pk_bf16_f32 v93, v93, v94
	v_cvt_pk_bf16_f32 v94, v88, v89
	v_add_f32_e32 v88, 1.0, v90
	v_add_f32_e32 v89, 1.0, v91
	v_cvt_pk_bf16_f32 v85, v85, v86
	v_cvt_pk_bf16_f32 v86, v80, v81
	v_add_f32_e32 v80, 1.0, v82
	v_add_f32_e32 v81, 1.0, v83
	v_min_f32_e32 v10, 0x7149f2ca, v10
	v_min_f32_e32 v11, 0x7149f2ca, v11
	v_min_f32_e32 v122, 0x7149f2ca, v122
	v_min_f32_e32 v123, 0x7149f2ca, v123
	v_min_f32_e32 v114, 0x7149f2ca, v114
	v_min_f32_e32 v115, 0x7149f2ca, v115
	v_min_f32_e32 v106, 0x7149f2ca, v106
	v_min_f32_e32 v107, 0x7149f2ca, v107
	v_min_f32_e32 v98, 0x7149f2ca, v98
	v_min_f32_e32 v99, 0x7149f2ca, v99
	v_min_f32_e32 v88, 0x7149f2ca, v88
	v_min_f32_e32 v89, 0x7149f2ca, v89
	v_min_f32_e32 v80, 0x7149f2ca, v80
	v_min_f32_e32 v81, 0x7149f2ca, v81
	v_cvt_pk_bf16_f32 v10, v10, v11
	v_add_f32_e32 v11, 1.0, v13
	v_add_f32_e32 v13, 1.0, v14
	v_cvt_pk_bf16_f32 v129, v122, v123
	v_add_u32_e32 v122, 0x800, v142
	v_cvt_pk_bf16_f32 v121, v114, v115
	v_add_u32_e32 v114, 0x1000, v142
	v_cvt_pk_bf16_f32 v113, v106, v107
	v_add_u32_e32 v106, 0x1800, v142
	v_cvt_pk_bf16_f32 v105, v98, v99
	v_add_u32_e32 v98, 0x2000, v142
	v_cvt_pk_bf16_f32 v95, v88, v89
	v_add_u32_e32 v88, 0x2800, v142
	v_cvt_pk_bf16_f32 v87, v80, v81
	v_add_u32_e32 v80, 0x3000, v142
	v_min_f32_e32 v11, 0x7149f2ca, v11
	v_min_f32_e32 v13, 0x7149f2ca, v13
	global_store_dwordx4 v142, v[126:129], s[54:55] sc0
	global_store_dwordx4 v122, v[118:121], s[54:55] sc0
	global_store_dwordx4 v114, v[110:113], s[54:55] sc0
	global_store_dwordx4 v106, v[102:105], s[54:55] sc0
; __device__ __forceinline__ float sigm(float v) { return __builtin_amdgcn_rcpf(1.0f + __builtin_amdgcn_exp2f(-LOG2E * v)); }
; __device__ __forceinline__ unsigned cvt_pk_bf16(float lo, float hi) { f32x2_t v = {lo, hi}; bf16x2_t b = __builtin_convertvector(v, bf16x2_t); return __builtin_bit_cast(unsigned, b); }
; template <int MODE> __device__ __forceinline__ float actf(float v) {
;     if (MODE == 1) return v * sigm(v);
;     if (MODE == 2) return fminf(1.0f + __builtin_amdgcn_exp2f(-LOG2E * v), 1e30f);
;     template <int MODE> __device__ __forceinline__ void run(const f32x4 (&acc)[2][2][4][2], const Unit& u, int wr, int wc, int fr, int fq) const {
;     ...
;         for (int bj = 0; bj < 2; ++bj) {
; #pragma unroll
;             for (int ai = 0; ai < 2; ++ai)
; #pragma unroll
;                 for (int m = 0; m < 4; ++m) { const unsigned off = off0 + ((MODE == 2) ? (unsigned)(((ai * 4 + m) * 2 + bj) * 1024) : (unsigned)((ai * HALF + m * 16) * 512 + bj * HALF) * 2u);
;                     const f32x4 v0 = acc[ai][bj][m][0], v1 = acc[ai][bj][m][1];
;                     u32x4 w; w.x = cvt_pk_bf16(actf<MODE>(v0[0]), actf<MODE>(v0[1])); w.y = cvt_pk_bf16(actf<MODE>(v0[2]), actf<MODE>(v0[3]));
;                     w.z = cvt_pk_bf16(actf<MODE>(v1[0]), actf<MODE>(v1[1])); w.w = cvt_pk_bf16(actf<MODE>(v1[2]), actf<MODE>(v1[3]));
;                     *(u32x4*)(base + off) = w; }
	global_store_dwordx4 v98, v[92:95], s[54:55] sc0
	global_store_dwordx4 v88, v[84:87], s[54:55] sc0
	global_store_dwordx4 v80, v[76:79], s[54:55] sc0
	v_add_u32_e32 v12, 0x400, v142
	v_cvt_pk_bf16_f32 v11, v11, v13
	global_store_dwordx4 v12, v[8:11], s[54:55] sc0
	v_mul_f32_e32 v13, 0xbfb8aa3b, v57
	v_exp_f32_e32 v13, v13
	v_mul_f32_e32 v8, 0xbfb8aa3b, v60
	v_mul_f32_e32 v9, 0xbfb8aa3b, v61
	v_exp_f32_e32 v8, v8
	v_exp_f32_e32 v9, v9
	v_mul_f32_e32 v10, 0xbfb8aa3b, v62
	v_mul_f32_e32 v11, 0xbfb8aa3b, v63
	v_exp_f32_e32 v10, v10
	v_exp_f32_e32 v11, v11
	v_add_f32_e32 v8, 1.0, v8
	v_add_f32_e32 v9, 1.0, v9
	v_min_f32_e32 v8, 0x7149f2ca, v8
	v_min_f32_e32 v9, 0x7149f2ca, v9
	v_cvt_pk_bf16_f32 v8, v8, v9
	v_add_f32_e32 v9, 1.0, v10
	v_add_f32_e32 v10, 1.0, v11
	v_mul_f32_e32 v11, 0xbfb8aa3b, v56
	v_exp_f32_e32 v11, v11
	v_min_f32_e32 v9, 0x7149f2ca, v9
	v_min_f32_e32 v10, 0x7149f2ca, v10
	v_cvt_pk_bf16_f32 v9, v9, v10
	v_add_f32_e32 v10, 1.0, v11
	v_add_f32_e32 v11, 1.0, v13
	v_mul_f32_e32 v13, 0xbfb8aa3b, v58
	v_mul_f32_e32 v14, 0xbfb8aa3b, v59
	v_exp_f32_e32 v13, v13
	v_exp_f32_e32 v14, v14
	v_min_f32_e32 v10, 0x7149f2ca, v10
	v_min_f32_e32 v11, 0x7149f2ca, v11
	v_cvt_pk_bf16_f32 v10, v10, v11
	v_add_f32_e32 v11, 1.0, v13
	v_add_f32_e32 v13, 1.0, v14
	v_min_f32_e32 v11, 0x7149f2ca, v11
	v_min_f32_e32 v13, 0x7149f2ca, v13
	v_add_u32_e32 v12, 0xc00, v142
	v_cvt_pk_bf16_f32 v11, v11, v13
	global_store_dwordx4 v12, v[8:11], s[54:55] sc0
	v_mul_f32_e32 v13, 0xbfb8aa3b, v49
	v_exp_f32_e32 v13, v13
	v_mul_f32_e32 v8, 0xbfb8aa3b, v52
	v_mul_f32_e32 v9, 0xbfb8aa3b, v53
	v_exp_f32_e32 v8, v8
	v_exp_f32_e32 v9, v9
	v_mul_f32_e32 v10, 0xbfb8aa3b, v54
	v_mul_f32_e32 v11, 0xbfb8aa3b, v55
	v_exp_f32_e32 v10, v10
	v_exp_f32_e32 v11, v11
	v_add_f32_e32 v8, 1.0, v8
	v_add_f32_e32 v9, 1.0, v9
	v_min_f32_e32 v8, 0x7149f2ca, v8
	v_min_f32_e32 v9, 0x7149f2ca, v9
	v_cvt_pk_bf16_f32 v8, v8, v9
	v_add_f32_e32 v9, 1.0, v10
	v_add_f32_e32 v10, 1.0, v11
	v_mul_f32_e32 v11, 0xbfb8aa3b, v48
	v_exp_f32_e32 v11, v11
	v_min_f32_e32 v9, 0x7149f2ca, v9
	v_min_f32_e32 v10, 0x7149f2ca, v10
	v_cvt_pk_bf16_f32 v9, v9, v10
	v_add_f32_e32 v10, 1.0, v11
	v_add_f32_e32 v11, 1.0, v13
	v_mul_f32_e32 v13, 0xbfb8aa3b, v50
	v_mul_f32_e32 v14, 0xbfb8aa3b, v51
	v_exp_f32_e32 v13, v13
	v_exp_f32_e32 v14, v14
	v_min_f32_e32 v10, 0x7149f2ca, v10
	v_min_f32_e32 v11, 0x7149f2ca, v11
	v_cvt_pk_bf16_f32 v10, v10, v11
	v_add_f32_e32 v11, 1.0, v13
	v_add_f32_e32 v13, 1.0, v14
	v_min_f32_e32 v11, 0x7149f2ca, v11
	v_min_f32_e32 v13, 0x7149f2ca, v13
	v_add_u32_e32 v12, 0x1400, v142
	v_cvt_pk_bf16_f32 v11, v11, v13
	global_store_dwordx4 v12, v[8:11], s[54:55] sc0
	v_mul_f32_e32 v13, 0xbfb8aa3b, v41
	v_exp_f32_e32 v13, v13
	v_mul_f32_e32 v8, 0xbfb8aa3b, v44
	v_mul_f32_e32 v9, 0xbfb8aa3b, v45
	v_exp_f32_e32 v8, v8
	v_exp_f32_e32 v9, v9
	v_mul_f32_e32 v10, 0xbfb8aa3b, v46
	v_mul_f32_e32 v11, 0xbfb8aa3b, v47
	v_exp_f32_e32 v10, v10
	v_exp_f32_e32 v11, v11
	v_add_f32_e32 v8, 1.0, v8
	v_add_f32_e32 v9, 1.0, v9
	v_min_f32_e32 v8, 0x7149f2ca, v8
	v_min_f32_e32 v9, 0x7149f2ca, v9
	v_cvt_pk_bf16_f32 v8, v8, v9
	v_add_f32_e32 v9, 1.0, v10
	v_add_f32_e32 v10, 1.0, v11
	v_mul_f32_e32 v11, 0xbfb8aa3b, v40
	v_exp_f32_e32 v11, v11
	v_min_f32_e32 v9, 0x7149f2ca, v9
	v_min_f32_e32 v10, 0x7149f2ca, v10
	v_cvt_pk_bf16_f32 v9, v9, v10
	v_add_f32_e32 v10, 1.0, v11
	v_add_f32_e32 v11, 1.0, v13
	v_mul_f32_e32 v13, 0xbfb8aa3b, v42
	v_mul_f32_e32 v14, 0xbfb8aa3b, v43
	v_exp_f32_e32 v13, v13
	v_exp_f32_e32 v14, v14
	v_min_f32_e32 v10, 0x7149f2ca, v10
	v_min_f32_e32 v11, 0x7149f2ca, v11
	v_cvt_pk_bf16_f32 v10, v10, v11
	v_add_f32_e32 v11, 1.0, v13
	v_add_f32_e32 v13, 1.0, v14
	v_min_f32_e32 v11, 0x7149f2ca, v11
	v_min_f32_e32 v13, 0x7149f2ca, v13
	v_add_u32_e32 v12, 0x1c00, v142
	v_cvt_pk_bf16_f32 v11, v11, v13
	global_store_dwordx4 v12, v[8:11], s[54:55] sc0
	v_mul_f32_e32 v13, 0xbfb8aa3b, v33
	v_exp_f32_e32 v13, v13
	v_mul_f32_e32 v8, 0xbfb8aa3b, v36
	v_mul_f32_e32 v9, 0xbfb8aa3b, v37
	v_exp_f32_e32 v8, v8
	v_exp_f32_e32 v9, v9
	v_mul_f32_e32 v10, 0xbfb8aa3b, v38
	v_mul_f32_e32 v11, 0xbfb8aa3b, v39
	v_exp_f32_e32 v10, v10
	v_exp_f32_e32 v11, v11
	v_add_f32_e32 v8, 1.0, v8
	v_add_f32_e32 v9, 1.0, v9
	v_min_f32_e32 v8, 0x7149f2ca, v8
	v_min_f32_e32 v9, 0x7149f2ca, v9
	v_cvt_pk_bf16_f32 v8, v8, v9
; __device__ __forceinline__ float sigm(float v) { return __builtin_amdgcn_rcpf(1.0f + __builtin_amdgcn_exp2f(-LOG2E * v)); }
; __device__ __forceinline__ unsigned cvt_pk_bf16(float lo, float hi) { f32x2_t v = {lo, hi}; bf16x2_t b = __builtin_convertvector(v, bf16x2_t); return __builtin_bit_cast(unsigned, b); }
; template <int MODE> __device__ __forceinline__ float actf(float v) {
;     if (MODE == 1) return v * sigm(v);
;     if (MODE == 2) return fminf(1.0f + __builtin_amdgcn_exp2f(-LOG2E * v), 1e30f);
;     template <int MODE> __device__ __forceinline__ void run(const f32x4 (&acc)[2][2][4][2], const Unit& u, int wr, int wc, int fr, int fq) const {
;     ...
;         for (int bj = 0; bj < 2; ++bj) {
; #pragma unroll
;             for (int ai = 0; ai < 2; ++ai)
; #pragma unroll
;                 for (int m = 0; m < 4; ++m) { const unsigned off = off0 + ((MODE == 2) ? (unsigned)(((ai * 4 + m) * 2 + bj) * 1024) : (unsigned)((ai * HALF + m * 16) * 512 + bj * HALF) * 2u);
;                     const f32x4 v0 = acc[ai][bj][m][0], v1 = acc[ai][bj][m][1];
;                     u32x4 w; w.x = cvt_pk_bf16(actf<MODE>(v0[0]), actf<MODE>(v0[1])); w.y = cvt_pk_bf16(actf<MODE>(v0[2]), actf<MODE>(v0[3]));
;                     w.z = cvt_pk_bf16(actf<MODE>(v1[0]), actf<MODE>(v1[1])); w.w = cvt_pk_bf16(actf<MODE>(v1[2]), actf<MODE>(v1[3]));
;                     *(u32x4*)(base + off) = w; }
	v_add_f32_e32 v9, 1.0, v10
	v_add_f32_e32 v10, 1.0, v11
	v_mul_f32_e32 v11, 0xbfb8aa3b, v32
	v_exp_f32_e32 v11, v11
	v_min_f32_e32 v9, 0x7149f2ca, v9
	v_min_f32_e32 v10, 0x7149f2ca, v10
	v_cvt_pk_bf16_f32 v9, v9, v10
	v_add_f32_e32 v10, 1.0, v11
	v_add_f32_e32 v11, 1.0, v13
	v_mul_f32_e32 v13, 0xbfb8aa3b, v34
	v_mul_f32_e32 v14, 0xbfb8aa3b, v35
	v_exp_f32_e32 v13, v13
	v_exp_f32_e32 v14, v14
	v_min_f32_e32 v10, 0x7149f2ca, v10
	v_min_f32_e32 v11, 0x7149f2ca, v11
	v_cvt_pk_bf16_f32 v10, v10, v11
	v_add_f32_e32 v11, 1.0, v13
	v_add_f32_e32 v13, 1.0, v14
	v_min_f32_e32 v11, 0x7149f2ca, v11
	v_min_f32_e32 v13, 0x7149f2ca, v13
	v_add_u32_e32 v12, 0x2400, v142
	v_cvt_pk_bf16_f32 v11, v11, v13
	global_store_dwordx4 v12, v[8:11], s[54:55] sc0
	v_mul_f32_e32 v13, 0xbfb8aa3b, v25
	v_exp_f32_e32 v13, v13
	v_mul_f32_e32 v8, 0xbfb8aa3b, v28
	v_mul_f32_e32 v9, 0xbfb8aa3b, v29
	v_exp_f32_e32 v8, v8
	v_exp_f32_e32 v9, v9
	v_mul_f32_e32 v10, 0xbfb8aa3b, v30
	v_mul_f32_e32 v11, 0xbfb8aa3b, v31
	v_exp_f32_e32 v10, v10
	v_exp_f32_e32 v11, v11
	v_add_f32_e32 v8, 1.0, v8
	v_add_f32_e32 v9, 1.0, v9
	v_min_f32_e32 v8, 0x7149f2ca, v8
	v_min_f32_e32 v9, 0x7149f2ca, v9
	v_cvt_pk_bf16_f32 v8, v8, v9
	v_add_f32_e32 v9, 1.0, v10
	v_add_f32_e32 v10, 1.0, v11
	v_mul_f32_e32 v11, 0xbfb8aa3b, v24
	v_exp_f32_e32 v11, v11
	v_min_f32_e32 v9, 0x7149f2ca, v9
	v_min_f32_e32 v10, 0x7149f2ca, v10
	v_cvt_pk_bf16_f32 v9, v9, v10
	v_add_f32_e32 v10, 1.0, v11
	v_add_f32_e32 v11, 1.0, v13
	v_mul_f32_e32 v13, 0xbfb8aa3b, v26
	v_mul_f32_e32 v14, 0xbfb8aa3b, v27
	v_exp_f32_e32 v13, v13
	v_exp_f32_e32 v14, v14
	v_min_f32_e32 v10, 0x7149f2ca, v10
	v_min_f32_e32 v11, 0x7149f2ca, v11
	v_cvt_pk_bf16_f32 v10, v10, v11
	v_add_f32_e32 v11, 1.0, v13
	v_add_f32_e32 v13, 1.0, v14
	v_min_f32_e32 v11, 0x7149f2ca, v11
	v_min_f32_e32 v13, 0x7149f2ca, v13
	v_add_u32_e32 v12, 0x2c00, v142
	v_cvt_pk_bf16_f32 v11, v11, v13
	global_store_dwordx4 v12, v[8:11], s[54:55] sc0
	v_mul_f32_e32 v13, 0xbfb8aa3b, v17
	v_exp_f32_e32 v13, v13
	v_mul_f32_e32 v8, 0xbfb8aa3b, v20
	v_mul_f32_e32 v9, 0xbfb8aa3b, v21
	v_exp_f32_e32 v8, v8
	v_exp_f32_e32 v9, v9
	v_mul_f32_e32 v10, 0xbfb8aa3b, v22
	v_mul_f32_e32 v11, 0xbfb8aa3b, v23
	v_exp_f32_e32 v10, v10
	v_exp_f32_e32 v11, v11
	v_add_f32_e32 v8, 1.0, v8
	v_add_f32_e32 v9, 1.0, v9
	v_min_f32_e32 v8, 0x7149f2ca, v8
	v_min_f32_e32 v9, 0x7149f2ca, v9
	v_cvt_pk_bf16_f32 v8, v8, v9
	v_add_f32_e32 v9, 1.0, v10
	v_add_f32_e32 v10, 1.0, v11
	v_mul_f32_e32 v11, 0xbfb8aa3b, v16
	v_exp_f32_e32 v11, v11
	v_mul_f32_e32 v4, 0xbfb8aa3b, v4
	v_mul_f32_e32 v5, 0xbfb8aa3b, v5
	v_exp_f32_e32 v4, v4
	v_exp_f32_e32 v5, v5
	v_min_f32_e32 v9, 0x7149f2ca, v9
	v_min_f32_e32 v10, 0x7149f2ca, v10
	v_mul_f32_e32 v6, 0xbfb8aa3b, v6
	v_mul_f32_e32 v7, 0xbfb8aa3b, v7
	v_mul_f32_e32 v0, 0xbfb8aa3b, v0
	v_mul_f32_e32 v1, 0xbfb8aa3b, v1
	v_cvt_pk_bf16_f32 v9, v9, v10
	v_add_f32_e32 v10, 1.0, v11
	v_add_f32_e32 v11, 1.0, v13
	v_mul_f32_e32 v13, 0xbfb8aa3b, v18
	v_mul_f32_e32 v14, 0xbfb8aa3b, v19
	v_exp_f32_e32 v6, v6
	v_exp_f32_e32 v7, v7
	v_exp_f32_e32 v0, v0
	v_exp_f32_e32 v1, v1
	v_exp_f32_e32 v13, v13
	v_exp_f32_e32 v14, v14
	v_mul_f32_e32 v2, 0xbfb8aa3b, v2
	v_mul_f32_e32 v3, 0xbfb8aa3b, v3
	v_add_f32_e32 v4, 1.0, v4
	v_add_f32_e32 v5, 1.0, v5
	v_exp_f32_e32 v2, v2
	v_exp_f32_e32 v3, v3
	v_min_f32_e32 v4, 0x7149f2ca, v4
	v_min_f32_e32 v5, 0x7149f2ca, v5
	v_min_f32_e32 v10, 0x7149f2ca, v10
	v_min_f32_e32 v11, 0x7149f2ca, v11
	v_cvt_pk_bf16_f32 v4, v4, v5
	v_add_f32_e32 v5, 1.0, v6
	v_add_f32_e32 v6, 1.0, v7
	v_add_f32_e32 v0, 1.0, v0
	v_add_f32_e32 v1, 1.0, v1
	v_cvt_pk_bf16_f32 v10, v10, v11
	v_add_f32_e32 v11, 1.0, v13
	v_add_f32_e32 v13, 1.0, v14
	v_min_f32_e32 v5, 0x7149f2ca, v5
	v_min_f32_e32 v6, 0x7149f2ca, v6
	v_min_f32_e32 v0, 0x7149f2ca, v0
	v_min_f32_e32 v1, 0x7149f2ca, v1
	v_min_f32_e32 v11, 0x7149f2ca, v11
	v_min_f32_e32 v13, 0x7149f2ca, v13
	v_cvt_pk_bf16_f32 v5, v5, v6
	v_cvt_pk_bf16_f32 v6, v0, v1
	v_add_f32_e32 v0, 1.0, v2
	v_add_f32_e32 v1, 1.0, v3
	v_add_u32_e32 v12, 0x3400, v142
	v_cvt_pk_bf16_f32 v11, v11, v13
	v_min_f32_e32 v0, 0x7149f2ca, v0
	v_min_f32_e32 v1, 0x7149f2ca, v1
	global_store_dwordx4 v12, v[8:11], s[54:55] sc0
	v_cvt_pk_bf16_f32 v7, v0, v1
	s_nop 0
	v_add_u32_e32 v8, 0x3c00, v142
	global_store_dwordx4 v8, v[4:7], s[54:55] sc0
